# cross-attention: each score tile normalised in place by its workgroup right after the scores epilogue; the separate normalisation pass is empty
# baseline (speedup 1.0000x reference)
; __device__ __forceinline__ void unpack8(u32x4 w, float* v) { v[0] = bflo(w.x); v[1] = bfhi(w.x); v[2] = bflo(w.y); v[3] = bfhi(w.y); v[4] = bflo(w.z); v[5] = bfhi(w.z); v[6] = bflo(w.w); v[7] = bfhi(w.w); }
; __device__ __forceinline__ void st8_bf16(bf16_t* p, const float* v) { *(u32x4*)p = pack8(v); }
; #define WSL() ({ GAS unsigned char* w_ = (GAS unsigned char*)p.ws; asm volatile("" : "+s"(w_)); (unsigned char*)w_; })
; #define IDS() const int tid = ltid(), lane = tid & 63, wave = tid >> 6, bx = lbid(), G = lgdim(); (void)lane; (void)wave; (void)bx; (void)G; (void)tid
; __global__ void __launch_bounds__(512, 2) fwd_megakernel(Params p) {
;     ...
;         { IDS(); unsigned char* ws = WSL(); bf16_t* PB = (bf16_t*)(ws + A_P); const float* LS = (const float*)(ws + A_LSUM);
;           const size_t NTH = (size_t)G * 512;
;           for (size_t i0 = (size_t)bx * 512 + tid; i0 < (size_t)M * DM / 8; i0 += 2 * NTH) {
;             f32x4 a[2], b[2]; u32x4 pw[2];
; #pragma unroll
;             for (int q = 0; q < 2; ++q) { const size_t i = i0 + q * NTH; const size_t row = i >> 7; const int c8 = (int)(i & 127) * 8, hd = c8 >> 8; const float* lp = LS + row * 32 + hd * 8;
;                 a[q] = *(const f32x4*)lp; b[q] = *(const f32x4*)(lp + 4); pw[q] = *(const u32x4*)(PB + i * 8); }
; #pragma unroll
;             for (int q = 0; q < 2; ++q) { const size_t i = i0 + q * NTH; const float inv = __builtin_amdgcn_rcpf(((a[q][0] + a[q][1]) + (a[q][2] + a[q][3])) + ((b[q][0] + b[q][1]) + (b[q][2] + b[q][3])));
;                 float v[8]; unpack8(pw[q], v);
; #pragma unroll
;                 for (int e = 0; e < 8; ++e) v[e] *= inv;
;                 st8_bf16(PB + i * 8, v); }
.LBB0_1674:
	s_or_b64 exec, exec, s[6:7]
	s_waitcnt vmcnt(0)
	s_barrier
	v_lshrrev_b32_e32 v0, 5, v214
	v_and_b32_e32 v1, 31, v214
	v_lshl_add_u32 v0, s56, 8, v0
	v_lshlrev_b32_e32 v2, 11, v0
	v_lshl_add_u32 v2, s34, 9, v2
	v_lshl_add_u32 v2, v1, 4, v2
	v_lshlrev_b32_e32 v3, 7, v0
	v_lshl_add_u32 v3, s34, 5, v3
	v_mov_b32_e32 v4, v2
	global_load_dwordx4 v[8:11], v2, s[14:15]
	global_load_dwordx4 v[40:43], v3, s[16:17]
	global_load_dwordx4 v[44:47], v3, s[16:17] offset:16
	v_add_u32_e32 v2, 0x8000, v2
	v_add_u32_e32 v3, 0x800, v3
	global_load_dwordx4 v[12:15], v2, s[14:15]
	global_load_dwordx4 v[48:51], v3, s[16:17]
	global_load_dwordx4 v[52:55], v3, s[16:17] offset:16
	v_add_u32_e32 v2, 0x8000, v2
	v_add_u32_e32 v3, 0x800, v3
	global_load_dwordx4 v[16:19], v2, s[14:15]
	global_load_dwordx4 v[56:59], v3, s[16:17]
	global_load_dwordx4 v[60:63], v3, s[16:17] offset:16
	v_add_u32_e32 v2, 0x8000, v2
	v_add_u32_e32 v3, 0x800, v3
	global_load_dwordx4 v[20:23], v2, s[14:15]
	global_load_dwordx4 v[64:67], v3, s[16:17]
	global_load_dwordx4 v[68:71], v3, s[16:17] offset:16
	v_add_u32_e32 v2, 0x8000, v2
	v_add_u32_e32 v3, 0x800, v3
	global_load_dwordx4 v[24:27], v2, s[14:15]
	global_load_dwordx4 v[72:75], v3, s[16:17]
	global_load_dwordx4 v[76:79], v3, s[16:17] offset:16
	v_add_u32_e32 v2, 0x8000, v2
	v_add_u32_e32 v3, 0x800, v3
	global_load_dwordx4 v[28:31], v2, s[14:15]
	global_load_dwordx4 v[80:83], v3, s[16:17]
	global_load_dwordx4 v[84:87], v3, s[16:17] offset:16
	v_add_u32_e32 v2, 0x8000, v2
	v_add_u32_e32 v3, 0x800, v3
	global_load_dwordx4 v[32:35], v2, s[14:15]
	global_load_dwordx4 v[88:91], v3, s[16:17]
	global_load_dwordx4 v[92:95], v3, s[16:17] offset:16
	v_add_u32_e32 v2, 0x8000, v2
	v_add_u32_e32 v3, 0x800, v3
	global_load_dwordx4 v[36:39], v2, s[14:15]
	global_load_dwordx4 v[96:99], v3, s[16:17]
	global_load_dwordx4 v[100:103], v3, s[16:17] offset:16
	v_add_u32_e32 v2, 0x8000, v2
	v_add_u32_e32 v3, 0x800, v3
	s_waitcnt vmcnt(21)
	v_add_f32_e32 v104, v40, v41
	v_add_f32_e32 v105, v42, v43
	v_add_f32_e32 v106, v44, v45
	v_add_f32_e32 v107, v46, v47
	v_add_f32_e32 v104, v104, v105
	v_add_f32_e32 v106, v106, v107
	v_add_f32_e32 v104, v104, v106
	v_rcp_f32_e32 v104, v104
	v_lshlrev_b32_e32 v108, 16, v8
	v_and_b32_e32 v109, 0xffff0000, v8
	v_lshlrev_b32_e32 v110, 16, v9
	v_and_b32_e32 v111, 0xffff0000, v9
	v_lshlrev_b32_e32 v112, 16, v10
	v_and_b32_e32 v113, 0xffff0000, v10
	v_lshlrev_b32_e32 v114, 16, v11
	v_and_b32_e32 v115, 0xffff0000, v11
	v_mul_f32_e32 v108, v104, v108
	v_mul_f32_e32 v109, v104, v109
	v_mul_f32_e32 v110, v104, v110
	v_mul_f32_e32 v111, v104, v111
	v_mul_f32_e32 v112, v104, v112
	v_mul_f32_e32 v113, v104, v113
	v_mul_f32_e32 v114, v104, v114
	v_mul_f32_e32 v115, v104, v115
	v_cvt_pk_bf16_f32 v8, v108, v109
	v_cvt_pk_bf16_f32 v9, v110, v111
	v_cvt_pk_bf16_f32 v10, v112, v113
	v_cvt_pk_bf16_f32 v11, v114, v115
	global_store_dwordx4 v4, v[8:11], s[14:15]
	v_add_u32_e32 v4, 0x8000, v4
	s_waitcnt vmcnt(18)
	v_add_f32_e32 v104, v48, v49
	v_add_f32_e32 v105, v50, v51
	v_add_f32_e32 v106, v52, v53
	v_add_f32_e32 v107, v54, v55
	v_add_f32_e32 v104, v104, v105
	v_add_f32_e32 v106, v106, v107
	v_add_f32_e32 v104, v104, v106
	v_rcp_f32_e32 v104, v104
	v_lshlrev_b32_e32 v108, 16, v12
	v_and_b32_e32 v109, 0xffff0000, v12
	v_lshlrev_b32_e32 v110, 16, v13
	v_and_b32_e32 v111, 0xffff0000, v13
	v_lshlrev_b32_e32 v112, 16, v14
	v_and_b32_e32 v113, 0xffff0000, v14
	v_lshlrev_b32_e32 v114, 16, v15
	v_and_b32_e32 v115, 0xffff0000, v15
	v_mul_f32_e32 v108, v104, v108
	v_mul_f32_e32 v109, v104, v109
	v_mul_f32_e32 v110, v104, v110
	v_mul_f32_e32 v111, v104, v111
	v_mul_f32_e32 v112, v104, v112
	v_mul_f32_e32 v113, v104, v113
	v_mul_f32_e32 v114, v104, v114
	v_mul_f32_e32 v115, v104, v115
	v_cvt_pk_bf16_f32 v12, v108, v109
	v_cvt_pk_bf16_f32 v13, v110, v111
	v_cvt_pk_bf16_f32 v14, v112, v113
	v_cvt_pk_bf16_f32 v15, v114, v115
	global_store_dwordx4 v4, v[12:15], s[14:15]
	v_add_u32_e32 v4, 0x8000, v4
	s_waitcnt vmcnt(15)
	v_add_f32_e32 v104, v56, v57
	v_add_f32_e32 v105, v58, v59
	v_add_f32_e32 v106, v60, v61
	v_add_f32_e32 v107, v62, v63
	v_add_f32_e32 v104, v104, v105
	v_add_f32_e32 v106, v106, v107
	v_add_f32_e32 v104, v104, v106
	v_rcp_f32_e32 v104, v104
	v_lshlrev_b32_e32 v108, 16, v16
	v_and_b32_e32 v109, 0xffff0000, v16
	v_lshlrev_b32_e32 v110, 16, v17
	v_and_b32_e32 v111, 0xffff0000, v17
	v_lshlrev_b32_e32 v112, 16, v18
	v_and_b32_e32 v113, 0xffff0000, v18
	v_lshlrev_b32_e32 v114, 16, v19
	v_and_b32_e32 v115, 0xffff0000, v19
	v_mul_f32_e32 v108, v104, v108
	v_mul_f32_e32 v109, v104, v109
	v_mul_f32_e32 v110, v104, v110
	v_mul_f32_e32 v111, v104, v111
	v_mul_f32_e32 v112, v104, v112
	v_mul_f32_e32 v113, v104, v113
	v_mul_f32_e32 v114, v104, v114
	v_mul_f32_e32 v115, v104, v115
	v_cvt_pk_bf16_f32 v16, v108, v109
	v_cvt_pk_bf16_f32 v17, v110, v111
	v_cvt_pk_bf16_f32 v18, v112, v113
	v_cvt_pk_bf16_f32 v19, v114, v115
	global_store_dwordx4 v4, v[16:19], s[14:15]
	v_add_u32_e32 v4, 0x8000, v4
	s_waitcnt vmcnt(12)
	v_add_f32_e32 v104, v64, v65
	v_add_f32_e32 v105, v66, v67
	v_add_f32_e32 v106, v68, v69
	v_add_f32_e32 v107, v70, v71
	v_add_f32_e32 v104, v104, v105
	v_add_f32_e32 v106, v106, v107
	v_add_f32_e32 v104, v104, v106
	v_rcp_f32_e32 v104, v104
	v_lshlrev_b32_e32 v108, 16, v20
	v_and_b32_e32 v109, 0xffff0000, v20
	v_lshlrev_b32_e32 v110, 16, v21
	v_and_b32_e32 v111, 0xffff0000, v21
	v_lshlrev_b32_e32 v112, 16, v22
	v_and_b32_e32 v113, 0xffff0000, v22
	v_lshlrev_b32_e32 v114, 16, v23
	v_and_b32_e32 v115, 0xffff0000, v23
	v_mul_f32_e32 v108, v104, v108
	v_mul_f32_e32 v109, v104, v109
	v_mul_f32_e32 v110, v104, v110
	v_mul_f32_e32 v111, v104, v111
	v_mul_f32_e32 v112, v104, v112
	v_mul_f32_e32 v113, v104, v113
	v_mul_f32_e32 v114, v104, v114
	v_mul_f32_e32 v115, v104, v115
	v_cvt_pk_bf16_f32 v20, v108, v109
	v_cvt_pk_bf16_f32 v21, v110, v111
	v_cvt_pk_bf16_f32 v22, v112, v113
	v_cvt_pk_bf16_f32 v23, v114, v115
	global_store_dwordx4 v4, v[20:23], s[14:15]
	v_add_u32_e32 v4, 0x8000, v4
	s_waitcnt vmcnt(9)
; __device__ __forceinline__ void unpack8(u32x4 w, float* v) { v[0] = bflo(w.x); v[1] = bfhi(w.x); v[2] = bflo(w.y); v[3] = bfhi(w.y); v[4] = bflo(w.z); v[5] = bfhi(w.z); v[6] = bflo(w.w); v[7] = bfhi(w.w); }
; __device__ __forceinline__ void st8_bf16(bf16_t* p, const float* v) { *(u32x4*)p = pack8(v); }
; __global__ void __launch_bounds__(512, 2) fwd_megakernel(Params p) {
;     ...
;           for (size_t i0 = (size_t)bx * 512 + tid; i0 < (size_t)M * DM / 8; i0 += 2 * NTH) {
;             f32x4 a[2], b[2]; u32x4 pw[2];
; #pragma unroll
;             for (int q = 0; q < 2; ++q) { const size_t i = i0 + q * NTH; const size_t row = i >> 7; const int c8 = (int)(i & 127) * 8, hd = c8 >> 8; const float* lp = LS + row * 32 + hd * 8;
;                 a[q] = *(const f32x4*)lp; b[q] = *(const f32x4*)(lp + 4); pw[q] = *(const u32x4*)(PB + i * 8); }
; #pragma unroll
;             for (int q = 0; q < 2; ++q) { const size_t i = i0 + q * NTH; const float inv = __builtin_amdgcn_rcpf(((a[q][0] + a[q][1]) + (a[q][2] + a[q][3])) + ((b[q][0] + b[q][1]) + (b[q][2] + b[q][3])));
;                 float v[8]; unpack8(pw[q], v);
; #pragma unroll
;                 for (int e = 0; e < 8; ++e) v[e] *= inv;
;                 st8_bf16(PB + i * 8, v); }
	v_add_f32_e32 v104, v72, v73
	v_add_f32_e32 v105, v74, v75
	v_add_f32_e32 v106, v76, v77
	v_add_f32_e32 v107, v78, v79
	v_add_f32_e32 v104, v104, v105
	v_add_f32_e32 v106, v106, v107
	v_add_f32_e32 v104, v104, v106
	v_rcp_f32_e32 v104, v104
	v_lshlrev_b32_e32 v108, 16, v24
	v_and_b32_e32 v109, 0xffff0000, v24
	v_lshlrev_b32_e32 v110, 16, v25
	v_and_b32_e32 v111, 0xffff0000, v25
	v_lshlrev_b32_e32 v112, 16, v26
	v_and_b32_e32 v113, 0xffff0000, v26
	v_lshlrev_b32_e32 v114, 16, v27
	v_and_b32_e32 v115, 0xffff0000, v27
	v_mul_f32_e32 v108, v104, v108
	v_mul_f32_e32 v109, v104, v109
	v_mul_f32_e32 v110, v104, v110
	v_mul_f32_e32 v111, v104, v111
	v_mul_f32_e32 v112, v104, v112
	v_mul_f32_e32 v113, v104, v113
	v_mul_f32_e32 v114, v104, v114
	v_mul_f32_e32 v115, v104, v115
	v_cvt_pk_bf16_f32 v24, v108, v109
	v_cvt_pk_bf16_f32 v25, v110, v111
	v_cvt_pk_bf16_f32 v26, v112, v113
	v_cvt_pk_bf16_f32 v27, v114, v115
	global_store_dwordx4 v4, v[24:27], s[14:15]
	v_add_u32_e32 v4, 0x8000, v4
	s_waitcnt vmcnt(6)
	v_add_f32_e32 v104, v80, v81
	v_add_f32_e32 v105, v82, v83
	v_add_f32_e32 v106, v84, v85
	v_add_f32_e32 v107, v86, v87
	v_add_f32_e32 v104, v104, v105
	v_add_f32_e32 v106, v106, v107
	v_add_f32_e32 v104, v104, v106
	v_rcp_f32_e32 v104, v104
	v_lshlrev_b32_e32 v108, 16, v28
	v_and_b32_e32 v109, 0xffff0000, v28
	v_lshlrev_b32_e32 v110, 16, v29
	v_and_b32_e32 v111, 0xffff0000, v29
	v_lshlrev_b32_e32 v112, 16, v30
	v_and_b32_e32 v113, 0xffff0000, v30
	v_lshlrev_b32_e32 v114, 16, v31
	v_and_b32_e32 v115, 0xffff0000, v31
	v_mul_f32_e32 v108, v104, v108
	v_mul_f32_e32 v109, v104, v109
	v_mul_f32_e32 v110, v104, v110
	v_mul_f32_e32 v111, v104, v111
	v_mul_f32_e32 v112, v104, v112
	v_mul_f32_e32 v113, v104, v113
	v_mul_f32_e32 v114, v104, v114
	v_mul_f32_e32 v115, v104, v115
	v_cvt_pk_bf16_f32 v28, v108, v109
	v_cvt_pk_bf16_f32 v29, v110, v111
	v_cvt_pk_bf16_f32 v30, v112, v113
	v_cvt_pk_bf16_f32 v31, v114, v115
	global_store_dwordx4 v4, v[28:31], s[14:15]
	v_add_u32_e32 v4, 0x8000, v4
	s_waitcnt vmcnt(3)
	v_add_f32_e32 v104, v88, v89
	v_add_f32_e32 v105, v90, v91
	v_add_f32_e32 v106, v92, v93
	v_add_f32_e32 v107, v94, v95
	v_add_f32_e32 v104, v104, v105
	v_add_f32_e32 v106, v106, v107
	v_add_f32_e32 v104, v104, v106
	v_rcp_f32_e32 v104, v104
	v_lshlrev_b32_e32 v108, 16, v32
	v_and_b32_e32 v109, 0xffff0000, v32
	v_lshlrev_b32_e32 v110, 16, v33
	v_and_b32_e32 v111, 0xffff0000, v33
	v_lshlrev_b32_e32 v112, 16, v34
	v_and_b32_e32 v113, 0xffff0000, v34
	v_lshlrev_b32_e32 v114, 16, v35
	v_and_b32_e32 v115, 0xffff0000, v35
	v_mul_f32_e32 v108, v104, v108
	v_mul_f32_e32 v109, v104, v109
	v_mul_f32_e32 v110, v104, v110
	v_mul_f32_e32 v111, v104, v111
	v_mul_f32_e32 v112, v104, v112
	v_mul_f32_e32 v113, v104, v113
	v_mul_f32_e32 v114, v104, v114
	v_mul_f32_e32 v115, v104, v115
	v_cvt_pk_bf16_f32 v32, v108, v109
	v_cvt_pk_bf16_f32 v33, v110, v111
	v_cvt_pk_bf16_f32 v34, v112, v113
	v_cvt_pk_bf16_f32 v35, v114, v115
	global_store_dwordx4 v4, v[32:35], s[14:15]
	v_add_u32_e32 v4, 0x8000, v4
	s_waitcnt vmcnt(0)
	v_add_f32_e32 v104, v96, v97
	v_add_f32_e32 v105, v98, v99
	v_add_f32_e32 v106, v100, v101
	v_add_f32_e32 v107, v102, v103
	v_add_f32_e32 v104, v104, v105
	v_add_f32_e32 v106, v106, v107
	v_add_f32_e32 v104, v104, v106
	v_rcp_f32_e32 v104, v104
	v_lshlrev_b32_e32 v108, 16, v36
	v_and_b32_e32 v109, 0xffff0000, v36
	v_lshlrev_b32_e32 v110, 16, v37
	v_and_b32_e32 v111, 0xffff0000, v37
	v_lshlrev_b32_e32 v112, 16, v38
	v_and_b32_e32 v113, 0xffff0000, v38
	v_lshlrev_b32_e32 v114, 16, v39
	v_and_b32_e32 v115, 0xffff0000, v39
	v_mul_f32_e32 v108, v104, v108
	v_mul_f32_e32 v109, v104, v109
	v_mul_f32_e32 v110, v104, v110
	v_mul_f32_e32 v111, v104, v111
	v_mul_f32_e32 v112, v104, v112
	v_mul_f32_e32 v113, v104, v113
	v_mul_f32_e32 v114, v104, v114
	v_mul_f32_e32 v115, v104, v115
	v_cvt_pk_bf16_f32 v36, v108, v109
	v_cvt_pk_bf16_f32 v37, v110, v111
	v_cvt_pk_bf16_f32 v38, v112, v113
	v_cvt_pk_bf16_f32 v39, v114, v115
	global_store_dwordx4 v4, v[36:39], s[14:15]
	v_add_u32_e32 v4, 0x8000, v4
	global_load_dwordx4 v[8:11], v2, s[14:15]
	global_load_dwordx4 v[40:43], v3, s[16:17]
	global_load_dwordx4 v[44:47], v3, s[16:17] offset:16
	v_add_u32_e32 v2, 0x8000, v2
	v_add_u32_e32 v3, 0x800, v3
	global_load_dwordx4 v[12:15], v2, s[14:15]
	global_load_dwordx4 v[48:51], v3, s[16:17]
	global_load_dwordx4 v[52:55], v3, s[16:17] offset:16
	v_add_u32_e32 v2, 0x8000, v2
	v_add_u32_e32 v3, 0x800, v3
	global_load_dwordx4 v[16:19], v2, s[14:15]
	global_load_dwordx4 v[56:59], v3, s[16:17]
	global_load_dwordx4 v[60:63], v3, s[16:17] offset:16
	v_add_u32_e32 v2, 0x8000, v2
	v_add_u32_e32 v3, 0x800, v3
	global_load_dwordx4 v[20:23], v2, s[14:15]
	global_load_dwordx4 v[64:67], v3, s[16:17]
	global_load_dwordx4 v[68:71], v3, s[16:17] offset:16
	v_add_u32_e32 v2, 0x8000, v2
	v_add_u32_e32 v3, 0x800, v3
	global_load_dwordx4 v[24:27], v2, s[14:15]
	global_load_dwordx4 v[72:75], v3, s[16:17]
	global_load_dwordx4 v[76:79], v3, s[16:17] offset:16
	v_add_u32_e32 v2, 0x8000, v2
	v_add_u32_e32 v3, 0x800, v3
	global_load_dwordx4 v[28:31], v2, s[14:15]
	global_load_dwordx4 v[80:83], v3, s[16:17]
	global_load_dwordx4 v[84:87], v3, s[16:17] offset:16
	v_add_u32_e32 v2, 0x8000, v2
	v_add_u32_e32 v3, 0x800, v3
	global_load_dwordx4 v[32:35], v2, s[14:15]
	global_load_dwordx4 v[88:91], v3, s[16:17]
	global_load_dwordx4 v[92:95], v3, s[16:17] offset:16
	v_add_u32_e32 v2, 0x8000, v2
	v_add_u32_e32 v3, 0x800, v3
	global_load_dwordx4 v[36:39], v2, s[14:15]
	global_load_dwordx4 v[96:99], v3, s[16:17]
	global_load_dwordx4 v[100:103], v3, s[16:17] offset:16
	v_add_u32_e32 v2, 0x8000, v2
	v_add_u32_e32 v3, 0x800, v3
	s_waitcnt vmcnt(21)
; __device__ __forceinline__ void unpack8(u32x4 w, float* v) { v[0] = bflo(w.x); v[1] = bfhi(w.x); v[2] = bflo(w.y); v[3] = bfhi(w.y); v[4] = bflo(w.z); v[5] = bfhi(w.z); v[6] = bflo(w.w); v[7] = bfhi(w.w); }
; __device__ __forceinline__ void st8_bf16(bf16_t* p, const float* v) { *(u32x4*)p = pack8(v); }
; __global__ void __launch_bounds__(512, 2) fwd_megakernel(Params p) {
;     ...
;           for (size_t i0 = (size_t)bx * 512 + tid; i0 < (size_t)M * DM / 8; i0 += 2 * NTH) {
;             f32x4 a[2], b[2]; u32x4 pw[2];
; #pragma unroll
;             for (int q = 0; q < 2; ++q) { const size_t i = i0 + q * NTH; const size_t row = i >> 7; const int c8 = (int)(i & 127) * 8, hd = c8 >> 8; const float* lp = LS + row * 32 + hd * 8;
;                 a[q] = *(const f32x4*)lp; b[q] = *(const f32x4*)(lp + 4); pw[q] = *(const u32x4*)(PB + i * 8); }
; #pragma unroll
;             for (int q = 0; q < 2; ++q) { const size_t i = i0 + q * NTH; const float inv = __builtin_amdgcn_rcpf(((a[q][0] + a[q][1]) + (a[q][2] + a[q][3])) + ((b[q][0] + b[q][1]) + (b[q][2] + b[q][3])));
;                 float v[8]; unpack8(pw[q], v);
; #pragma unroll
;                 for (int e = 0; e < 8; ++e) v[e] *= inv;
;                 st8_bf16(PB + i * 8, v); }
	v_add_f32_e32 v104, v40, v41
	v_add_f32_e32 v105, v42, v43
	v_add_f32_e32 v106, v44, v45
	v_add_f32_e32 v107, v46, v47
	v_add_f32_e32 v104, v104, v105
	v_add_f32_e32 v106, v106, v107
	v_add_f32_e32 v104, v104, v106
	v_rcp_f32_e32 v104, v104
	v_lshlrev_b32_e32 v108, 16, v8
	v_and_b32_e32 v109, 0xffff0000, v8
	v_lshlrev_b32_e32 v110, 16, v9
	v_and_b32_e32 v111, 0xffff0000, v9
	v_lshlrev_b32_e32 v112, 16, v10
	v_and_b32_e32 v113, 0xffff0000, v10
	v_lshlrev_b32_e32 v114, 16, v11
	v_and_b32_e32 v115, 0xffff0000, v11
	v_mul_f32_e32 v108, v104, v108
	v_mul_f32_e32 v109, v104, v109
	v_mul_f32_e32 v110, v104, v110
	v_mul_f32_e32 v111, v104, v111
	v_mul_f32_e32 v112, v104, v112
	v_mul_f32_e32 v113, v104, v113
	v_mul_f32_e32 v114, v104, v114
	v_mul_f32_e32 v115, v104, v115
	v_cvt_pk_bf16_f32 v8, v108, v109
	v_cvt_pk_bf16_f32 v9, v110, v111
	v_cvt_pk_bf16_f32 v10, v112, v113
	v_cvt_pk_bf16_f32 v11, v114, v115
	global_store_dwordx4 v4, v[8:11], s[14:15]
	v_add_u32_e32 v4, 0x8000, v4
	s_waitcnt vmcnt(18)
	v_add_f32_e32 v104, v48, v49
	v_add_f32_e32 v105, v50, v51
	v_add_f32_e32 v106, v52, v53
	v_add_f32_e32 v107, v54, v55
	v_add_f32_e32 v104, v104, v105
	v_add_f32_e32 v106, v106, v107
	v_add_f32_e32 v104, v104, v106
	v_rcp_f32_e32 v104, v104
	v_lshlrev_b32_e32 v108, 16, v12
	v_and_b32_e32 v109, 0xffff0000, v12
	v_lshlrev_b32_e32 v110, 16, v13
	v_and_b32_e32 v111, 0xffff0000, v13
	v_lshlrev_b32_e32 v112, 16, v14
	v_and_b32_e32 v113, 0xffff0000, v14
	v_lshlrev_b32_e32 v114, 16, v15
	v_and_b32_e32 v115, 0xffff0000, v15
	v_mul_f32_e32 v108, v104, v108
	v_mul_f32_e32 v109, v104, v109
	v_mul_f32_e32 v110, v104, v110
	v_mul_f32_e32 v111, v104, v111
	v_mul_f32_e32 v112, v104, v112
	v_mul_f32_e32 v113, v104, v113
	v_mul_f32_e32 v114, v104, v114
	v_mul_f32_e32 v115, v104, v115
	v_cvt_pk_bf16_f32 v12, v108, v109
	v_cvt_pk_bf16_f32 v13, v110, v111
	v_cvt_pk_bf16_f32 v14, v112, v113
	v_cvt_pk_bf16_f32 v15, v114, v115
	global_store_dwordx4 v4, v[12:15], s[14:15]
	v_add_u32_e32 v4, 0x8000, v4
	s_waitcnt vmcnt(15)
	v_add_f32_e32 v104, v56, v57
	v_add_f32_e32 v105, v58, v59
	v_add_f32_e32 v106, v60, v61
	v_add_f32_e32 v107, v62, v63
	v_add_f32_e32 v104, v104, v105
	v_add_f32_e32 v106, v106, v107
	v_add_f32_e32 v104, v104, v106
	v_rcp_f32_e32 v104, v104
	v_lshlrev_b32_e32 v108, 16, v16
	v_and_b32_e32 v109, 0xffff0000, v16
	v_lshlrev_b32_e32 v110, 16, v17
	v_and_b32_e32 v111, 0xffff0000, v17
	v_lshlrev_b32_e32 v112, 16, v18
	v_and_b32_e32 v113, 0xffff0000, v18
	v_lshlrev_b32_e32 v114, 16, v19
	v_and_b32_e32 v115, 0xffff0000, v19
	v_mul_f32_e32 v108, v104, v108
	v_mul_f32_e32 v109, v104, v109
	v_mul_f32_e32 v110, v104, v110
	v_mul_f32_e32 v111, v104, v111
	v_mul_f32_e32 v112, v104, v112
	v_mul_f32_e32 v113, v104, v113
	v_mul_f32_e32 v114, v104, v114
	v_mul_f32_e32 v115, v104, v115
	v_cvt_pk_bf16_f32 v16, v108, v109
	v_cvt_pk_bf16_f32 v17, v110, v111
	v_cvt_pk_bf16_f32 v18, v112, v113
	v_cvt_pk_bf16_f32 v19, v114, v115
	global_store_dwordx4 v4, v[16:19], s[14:15]
	v_add_u32_e32 v4, 0x8000, v4
	s_waitcnt vmcnt(12)
	v_add_f32_e32 v104, v64, v65
	v_add_f32_e32 v105, v66, v67
	v_add_f32_e32 v106, v68, v69
	v_add_f32_e32 v107, v70, v71
	v_add_f32_e32 v104, v104, v105
	v_add_f32_e32 v106, v106, v107
	v_add_f32_e32 v104, v104, v106
	v_rcp_f32_e32 v104, v104
	v_lshlrev_b32_e32 v108, 16, v20
	v_and_b32_e32 v109, 0xffff0000, v20
	v_lshlrev_b32_e32 v110, 16, v21
	v_and_b32_e32 v111, 0xffff0000, v21
	v_lshlrev_b32_e32 v112, 16, v22
	v_and_b32_e32 v113, 0xffff0000, v22
	v_lshlrev_b32_e32 v114, 16, v23
	v_and_b32_e32 v115, 0xffff0000, v23
	v_mul_f32_e32 v108, v104, v108
	v_mul_f32_e32 v109, v104, v109
	v_mul_f32_e32 v110, v104, v110
	v_mul_f32_e32 v111, v104, v111
	v_mul_f32_e32 v112, v104, v112
	v_mul_f32_e32 v113, v104, v113
	v_mul_f32_e32 v114, v104, v114
	v_mul_f32_e32 v115, v104, v115
	v_cvt_pk_bf16_f32 v20, v108, v109
	v_cvt_pk_bf16_f32 v21, v110, v111
	v_cvt_pk_bf16_f32 v22, v112, v113
	v_cvt_pk_bf16_f32 v23, v114, v115
	global_store_dwordx4 v4, v[20:23], s[14:15]
	v_add_u32_e32 v4, 0x8000, v4
	s_waitcnt vmcnt(9)
; __device__ __forceinline__ void unpack8(u32x4 w, float* v) { v[0] = bflo(w.x); v[1] = bfhi(w.x); v[2] = bflo(w.y); v[3] = bfhi(w.y); v[4] = bflo(w.z); v[5] = bfhi(w.z); v[6] = bflo(w.w); v[7] = bfhi(w.w); }
; __device__ __forceinline__ void st8_bf16(bf16_t* p, const float* v) { *(u32x4*)p = pack8(v); }
; __global__ void __launch_bounds__(512, 2) fwd_megakernel(Params p) {
;     ...
;           for (size_t i0 = (size_t)bx * 512 + tid; i0 < (size_t)M * DM / 8; i0 += 2 * NTH) {
;             f32x4 a[2], b[2]; u32x4 pw[2];
; #pragma unroll
;             for (int q = 0; q < 2; ++q) { const size_t i = i0 + q * NTH; const size_t row = i >> 7; const int c8 = (int)(i & 127) * 8, hd = c8 >> 8; const float* lp = LS + row * 32 + hd * 8;
;                 a[q] = *(const f32x4*)lp; b[q] = *(const f32x4*)(lp + 4); pw[q] = *(const u32x4*)(PB + i * 8); }
; #pragma unroll
;             for (int q = 0; q < 2; ++q) { const size_t i = i0 + q * NTH; const float inv = __builtin_amdgcn_rcpf(((a[q][0] + a[q][1]) + (a[q][2] + a[q][3])) + ((b[q][0] + b[q][1]) + (b[q][2] + b[q][3])));
;                 float v[8]; unpack8(pw[q], v);
; #pragma unroll
;                 for (int e = 0; e < 8; ++e) v[e] *= inv;
;                 st8_bf16(PB + i * 8, v); }
	v_add_f32_e32 v104, v72, v73
	v_add_f32_e32 v105, v74, v75
	v_add_f32_e32 v106, v76, v77
	v_add_f32_e32 v107, v78, v79
	v_add_f32_e32 v104, v104, v105
	v_add_f32_e32 v106, v106, v107
	v_add_f32_e32 v104, v104, v106
	v_rcp_f32_e32 v104, v104
	v_lshlrev_b32_e32 v108, 16, v24
	v_and_b32_e32 v109, 0xffff0000, v24
	v_lshlrev_b32_e32 v110, 16, v25
	v_and_b32_e32 v111, 0xffff0000, v25
	v_lshlrev_b32_e32 v112, 16, v26
	v_and_b32_e32 v113, 0xffff0000, v26
	v_lshlrev_b32_e32 v114, 16, v27
	v_and_b32_e32 v115, 0xffff0000, v27
	v_mul_f32_e32 v108, v104, v108
	v_mul_f32_e32 v109, v104, v109
	v_mul_f32_e32 v110, v104, v110
	v_mul_f32_e32 v111, v104, v111
	v_mul_f32_e32 v112, v104, v112
	v_mul_f32_e32 v113, v104, v113
	v_mul_f32_e32 v114, v104, v114
	v_mul_f32_e32 v115, v104, v115
	v_cvt_pk_bf16_f32 v24, v108, v109
	v_cvt_pk_bf16_f32 v25, v110, v111
	v_cvt_pk_bf16_f32 v26, v112, v113
	v_cvt_pk_bf16_f32 v27, v114, v115
	global_store_dwordx4 v4, v[24:27], s[14:15]
	v_add_u32_e32 v4, 0x8000, v4
	s_waitcnt vmcnt(6)
	v_add_f32_e32 v104, v80, v81
	v_add_f32_e32 v105, v82, v83
	v_add_f32_e32 v106, v84, v85
	v_add_f32_e32 v107, v86, v87
	v_add_f32_e32 v104, v104, v105
	v_add_f32_e32 v106, v106, v107
	v_add_f32_e32 v104, v104, v106
	v_rcp_f32_e32 v104, v104
	v_lshlrev_b32_e32 v108, 16, v28
	v_and_b32_e32 v109, 0xffff0000, v28
	v_lshlrev_b32_e32 v110, 16, v29
	v_and_b32_e32 v111, 0xffff0000, v29
	v_lshlrev_b32_e32 v112, 16, v30
	v_and_b32_e32 v113, 0xffff0000, v30
	v_lshlrev_b32_e32 v114, 16, v31
	v_and_b32_e32 v115, 0xffff0000, v31
	v_mul_f32_e32 v108, v104, v108
	v_mul_f32_e32 v109, v104, v109
	v_mul_f32_e32 v110, v104, v110
	v_mul_f32_e32 v111, v104, v111
	v_mul_f32_e32 v112, v104, v112
	v_mul_f32_e32 v113, v104, v113
	v_mul_f32_e32 v114, v104, v114
	v_mul_f32_e32 v115, v104, v115
	v_cvt_pk_bf16_f32 v28, v108, v109
	v_cvt_pk_bf16_f32 v29, v110, v111
	v_cvt_pk_bf16_f32 v30, v112, v113
	v_cvt_pk_bf16_f32 v31, v114, v115
	global_store_dwordx4 v4, v[28:31], s[14:15]
	v_add_u32_e32 v4, 0x8000, v4
	s_waitcnt vmcnt(3)
	v_add_f32_e32 v104, v88, v89
	v_add_f32_e32 v105, v90, v91
	v_add_f32_e32 v106, v92, v93
	v_add_f32_e32 v107, v94, v95
	v_add_f32_e32 v104, v104, v105
	v_add_f32_e32 v106, v106, v107
	v_add_f32_e32 v104, v104, v106
	v_rcp_f32_e32 v104, v104
	v_lshlrev_b32_e32 v108, 16, v32
	v_and_b32_e32 v109, 0xffff0000, v32
	v_lshlrev_b32_e32 v110, 16, v33
	v_and_b32_e32 v111, 0xffff0000, v33
	v_lshlrev_b32_e32 v112, 16, v34
	v_and_b32_e32 v113, 0xffff0000, v34
	v_lshlrev_b32_e32 v114, 16, v35
	v_and_b32_e32 v115, 0xffff0000, v35
	v_mul_f32_e32 v108, v104, v108
	v_mul_f32_e32 v109, v104, v109
	v_mul_f32_e32 v110, v104, v110
	v_mul_f32_e32 v111, v104, v111
	v_mul_f32_e32 v112, v104, v112
	v_mul_f32_e32 v113, v104, v113
	v_mul_f32_e32 v114, v104, v114
	v_mul_f32_e32 v115, v104, v115
	v_cvt_pk_bf16_f32 v32, v108, v109
	v_cvt_pk_bf16_f32 v33, v110, v111
	v_cvt_pk_bf16_f32 v34, v112, v113
	v_cvt_pk_bf16_f32 v35, v114, v115
	global_store_dwordx4 v4, v[32:35], s[14:15]
	v_add_u32_e32 v4, 0x8000, v4
	s_waitcnt vmcnt(0)
	v_add_f32_e32 v104, v96, v97
	v_add_f32_e32 v105, v98, v99
	v_add_f32_e32 v106, v100, v101
	v_add_f32_e32 v107, v102, v103
	v_add_f32_e32 v104, v104, v105
	v_add_f32_e32 v106, v106, v107
	v_add_f32_e32 v104, v104, v106
	v_rcp_f32_e32 v104, v104
	v_lshlrev_b32_e32 v108, 16, v36
	v_and_b32_e32 v109, 0xffff0000, v36
	v_lshlrev_b32_e32 v110, 16, v37
	v_and_b32_e32 v111, 0xffff0000, v37
	v_lshlrev_b32_e32 v112, 16, v38
	v_and_b32_e32 v113, 0xffff0000, v38
	v_lshlrev_b32_e32 v114, 16, v39
	v_and_b32_e32 v115, 0xffff0000, v39
	v_mul_f32_e32 v108, v104, v108
	v_mul_f32_e32 v109, v104, v109
	v_mul_f32_e32 v110, v104, v110
	v_mul_f32_e32 v111, v104, v111
	v_mul_f32_e32 v112, v104, v112
	v_mul_f32_e32 v113, v104, v113
	v_mul_f32_e32 v114, v104, v114
	v_mul_f32_e32 v115, v104, v115
	v_cvt_pk_bf16_f32 v36, v108, v109
	v_cvt_pk_bf16_f32 v37, v110, v111
	v_cvt_pk_bf16_f32 v38, v112, v113
	v_cvt_pk_bf16_f32 v39, v114, v115
	global_store_dwordx4 v4, v[36:39], s[14:15]
	v_add_u32_e32 v4, 0x8000, v4
	s_and_b64 vcc, exec, s[4:5]
	s_mov_b64 s[4:5], -1
	s_cbranch_vccnz .LBB0_1629
	s_andn2_b64 vcc, exec, s[12:13]
	s_cbranch_vccnz .LBB0_1628
	s_barrier
	s_branch .LBB0_1628

; #define WSL() ({ GAS unsigned char* w_ = (GAS unsigned char*)p.ws; asm volatile("" : "+s"(w_)); (unsigned char*)w_; })
; #define IDS() const int tid = ltid(), lane = tid & 63, wave = tid >> 6, bx = lbid(), G = lgdim(); (void)lane; (void)wave; (void)bx; (void)G; (void)tid
; __global__ void __launch_bounds__(512, 2) fwd_megakernel(Params p) {
;     ...
;         { IDS(); unsigned char* ws = WSL(); bf16_t* PB = (bf16_t*)(ws + A_P); const float* LS = (const float*)(ws + A_LSUM);
;           const size_t NTH = (size_t)G * 512;
;           for (size_t i0 = (size_t)bx * 512 + tid; i0 < (size_t)M * DM / 8; i0 += 2 * NTH) {
;             f32x4 a[2], b[2]; u32x4 pw[2];
; #pragma unroll
;             for (int q = 0; q < 2; ++q) { const size_t i = i0 + q * NTH; const size_t row = i >> 7; const int c8 = (int)(i & 127) * 8, hd = c8 >> 8; const float* lp = LS + row * 32 + hd * 8;
;                 a[q] = *(const f32x4*)lp; b[q] = *(const f32x4*)(lp + 4); pw[q] = *(const u32x4*)(PB + i * 8); }
.LBB0_1729:
	s_or_b64 exec, exec, s[4:5]
	s_waitcnt lgkmcnt(0)
	v_mov_b32_e32 v0, v214
	s_mov_b32 s14, s91
	s_barrier
	s_ashr_i32 s15, s14, 31
	s_lshl_b64 s[18:19], s[14:15], 9
	v_ashrrev_i32_e32 v1, 31, v0
	v_lshl_add_u64 v[24:25], s[18:19], 0, v[0:1]
	s_mov_b64 s[0:1], 0x400000
	s_mov_b32 s16, s92
	s_mov_b64 s[8:9], s[82:83]
	s_mov_b64 vcc, 0
	s_and_saveexec_b64 s[4:5], vcc
	s_cbranch_execz .LBB0_1732
	s_add_u32 s6, s8, 0x9c00000
	s_addc_u32 s7, s9, 0
	s_add_u32 s8, s8, 0xdc00000
	s_addc_u32 s9, s9, 0
	s_ashr_i32 s17, s16, 31
	s_lshl_b64 s[12:13], s[16:17], 9
	s_lshl_b64 s[0:1], s[14:15], 13
	s_lshl_b64 s[14:15], s[16:17], 14
	s_lshl_b64 s[16:17], s[16:17], 10
	v_lshl_add_u64 v[26:27], v[0:1], 4, s[0:1]
	s_add_u32 s0, s18, s12
	s_addc_u32 s1, s19, s13
	v_lshl_add_u64 v[0:1], s[0:1], 0, v[0:1]
	v_lshlrev_b64 v[28:29], 4, v[0:1]
	s_mov_b64 s[18:19], 0
